# P13 chunk loop decay-matrix stage: the 16 cumulative-decay LDS words are read up front and waited once instead of 16 guarded read+wait pairs
# baseline (speedup 1.0000x reference)
.LBB0_2475:
	s_or_b64 exec, exec, s[92:93]
	ds_read2_b64 v[66:69], v162 offset1:2
	v_cvt_pk_bf16_f32 v70, v50, v51
	v_cvt_pk_bf16_f32 v71, v52, v53
	v_cvt_pk_bf16_f32 v72, v54, v55
	v_cvt_pk_bf16_f32 v73, v56, v57
	ds_read2_b64 v[226:229], v162 offset0:4 offset1:6
	ds_read2_b64 v[234:237], v162 offset0:8 offset1:10
	ds_read2_b64 v[238:241], v162 offset0:12 offset1:14
	ds_read2_b64 v[246:249], v162 offset0:16 offset1:18
	v_cvt_pk_bf16_f32 v230, v58, v59
	v_cvt_pk_bf16_f32 v231, v60, v61
	v_cvt_pk_bf16_f32 v232, v62, v63
	s_waitcnt lgkmcnt(4)
	v_mfma_f32_32x32x16_bf16 v[66:81], v[66:69], v[70:73], 0
	v_cvt_pk_bf16_f32 v233, v64, v65
	s_waitcnt lgkmcnt(3)
	s_nop 0
	v_mfma_f32_32x32x16_bf16 v[66:81], v[226:229], v[230:233], v[66:81]
	ds_read2_b64 v[226:229], v162 offset0:20 offset1:22
	v_cvt_pk_bf16_f32 v230, v34, v35
	v_cvt_pk_bf16_f32 v231, v36, v37
	v_cvt_pk_bf16_f32 v232, v38, v39
	v_cvt_pk_bf16_f32 v233, v40, v41
	s_waitcnt lgkmcnt(3)
	s_nop 0
	v_mfma_f32_32x32x16_bf16 v[66:81], v[234:237], v[230:233], v[66:81]
	ds_read2_b64 v[234:237], v162 offset0:24 offset1:26
	v_cvt_pk_bf16_f32 v230, v42, v43
	v_cvt_pk_bf16_f32 v231, v44, v45
	v_cvt_pk_bf16_f32 v232, v46, v47
	v_cvt_pk_bf16_f32 v233, v48, v49
	s_waitcnt lgkmcnt(3)
	s_nop 0
	v_mfma_f32_32x32x16_bf16 v[66:81], v[238:241], v[230:233], v[66:81]
	ds_read2_b64 v[238:241], v162 offset0:28 offset1:30
	v_cvt_pk_bf16_f32 v230, v18, v19
	v_cvt_pk_bf16_f32 v231, v20, v21
	v_cvt_pk_bf16_f32 v232, v22, v23
	v_cvt_pk_bf16_f32 v233, v24, v25
	s_waitcnt lgkmcnt(3)
	s_nop 0
	v_mfma_f32_32x32x16_bf16 v[66:81], v[246:249], v[230:233], v[66:81]
	v_cvt_pk_bf16_f32 v230, v26, v27
	v_cvt_pk_bf16_f32 v231, v28, v29
	v_cvt_pk_bf16_f32 v232, v30, v31
	v_cvt_pk_bf16_f32 v233, v32, v33
	s_waitcnt lgkmcnt(2)
	s_nop 0
	v_mfma_f32_32x32x16_bf16 v[66:81], v[226:229], v[230:233], v[66:81]
	v_cvt_pk_bf16_f32 v230, v2, v3
	v_cvt_pk_bf16_f32 v231, v4, v5
	v_cvt_pk_bf16_f32 v232, v6, v7
	v_cvt_pk_bf16_f32 v233, v8, v9
	s_waitcnt lgkmcnt(1)
	s_nop 0
	v_mfma_f32_32x32x16_bf16 v[66:81], v[234:237], v[230:233], v[66:81]
	v_cvt_pk_bf16_f32 v230, v10, v11
	v_cvt_pk_bf16_f32 v231, v12, v13
	v_cvt_pk_bf16_f32 v232, v14, v15
	v_cvt_pk_bf16_f32 v233, v16, v17
	s_waitcnt lgkmcnt(0)
	s_barrier
	v_mfma_f32_32x32x16_bf16 v[66:81], v[238:241], v[230:233], v[66:81]
	s_and_saveexec_b64 s[92:93], s[24:25]
	s_xor_b64 vcc, exec, s[92:93]
	s_cbranch_execz .LBB0_2509
	ds_read_b32 v147, v169
	ds_read_b32 v139, v170
	ds_read_b32 v234, v181
	ds_read_b32 v235, v182
	ds_read_b32 v236, v183
	ds_read_b32 v237, v184
	ds_read_b32 v238, v185
	ds_read_b32 v239, v186
	ds_read_b32 v240, v187
	ds_read_b32 v241, v188
	ds_read_b32 v246, v189
	ds_read_b32 v247, v190
	ds_read_b32 v248, v191
	ds_read_b32 v249, v192
	s_waitcnt lgkmcnt(4)
	ds_read_b32 v250, v193
	ds_read_b32 v251, v194
	ds_read_b32 v252, v195
	ds_read_b32 v253, v196
	s_waitcnt lgkmcnt(0)
	v_mov_b32_e32 v151, 0
	v_mov_b32_e32 v155, 0
	s_and_saveexec_b64 s[92:93], s[10:11]
	s_cbranch_execz .LBB0_2478
	v_sub_f32_e32 v155, v234, v147
	v_mul_f32_e32 v155, 0x3fb8aa3b, v155
	v_exp_f32_e32 v155, v155
	s_nop 0
	v_mul_f32_e32 v82, v82, v155
	v_mul_f32_e32 v155, v139, v82
.LBB0_2478:
	s_or_b64 exec, exec, s[92:93]
	v_readlane_b32 s12, v245, 44
	v_add_f32_e32 v82, v219, v155
	v_readlane_b32 s13, v245, 45
	s_nop 1
	v_cndmask_b32_e64 v82, v155, v82, s[12:13]
	v_readlane_b32 s12, v244, 12
	v_cvt_pk_bf16_f32 v82, v82, s0
	v_readlane_b32 s13, v244, 13
	ds_write_b16 v217, v82 offset:17408
	s_and_saveexec_b64 s[92:93], s[12:13]
	s_cbranch_execz .LBB0_2480
	v_sub_f32_e32 v82, v235, v147
	v_mul_f32_e32 v82, 0x3fb8aa3b, v82
	v_exp_f32_e32 v82, v82
	s_nop 0
	v_mul_f32_e32 v82, v83, v82
	v_mul_f32_e32 v151, v139, v82
.LBB0_2480:
	s_or_b64 exec, exec, s[92:93]
	v_readlane_b32 s12, v244, 30
	v_add_f32_e32 v82, v219, v151
	v_readlane_b32 s13, v244, 31
	v_mov_b32_e32 v83, 0
	s_nop 0
	v_cndmask_b32_e64 v82, v151, v82, s[12:13]
	v_cvt_pk_bf16_f32 v82, v82, s0
	ds_write_b16 v217, v82 offset:17552
	v_mov_b32_e32 v82, 0
	s_and_saveexec_b64 s[92:93], s[26:27]
	s_cbranch_execz .LBB0_2482
	v_sub_f32_e32 v83, v236, v147
	v_mul_f32_e32 v83, 0x3fb8aa3b, v83
	v_exp_f32_e32 v83, v83
	s_nop 0
	v_mul_f32_e32 v83, v84, v83
	v_mul_f32_e32 v83, v139, v83
.LBB0_2482:
	s_or_b64 exec, exec, s[92:93]
	v_add_f32_e32 v84, v219, v83
	v_cndmask_b32_e64 v83, v83, v84, s[28:29]
	v_cvt_pk_bf16_f32 v83, v83, s0
	ds_write_b16 v217, v83 offset:17696
	s_and_saveexec_b64 s[92:93], s[30:31]
	s_cbranch_execz .LBB0_2484
	v_sub_f32_e32 v82, v237, v147
	v_mul_f32_e32 v82, 0x3fb8aa3b, v82
	v_exp_f32_e32 v82, v82
	s_nop 0
	v_mul_f32_e32 v82, v85, v82
	v_mul_f32_e32 v82, v139, v82
.LBB0_2484:
	s_or_b64 exec, exec, s[92:93]
	v_add_f32_e32 v83, v219, v82
	v_cndmask_b32_e64 v82, v82, v83, s[34:35]
	v_cvt_pk_bf16_f32 v82, v82, s0
	ds_write_b16 v217, v82 offset:17840
	v_mov_b32_e32 v82, 0
	v_mov_b32_e32 v83, 0
	s_and_saveexec_b64 s[92:93], s[36:37]
	s_cbranch_execz .LBB0_2486
	v_sub_f32_e32 v83, v238, v147
	v_mul_f32_e32 v83, 0x3fb8aa3b, v83
	v_exp_f32_e32 v83, v83
	s_nop 0
	v_mul_f32_e32 v83, v86, v83
	v_mul_f32_e32 v83, v139, v83
.LBB0_2486:
	s_or_b64 exec, exec, s[92:93]
	v_add_f32_e32 v84, v219, v83
	v_cndmask_b32_e64 v83, v83, v84, s[38:39]
	v_cvt_pk_bf16_f32 v83, v83, s0
	ds_write_b16 v217, v83 offset:18560
	s_and_saveexec_b64 s[92:93], s[40:41]
	s_cbranch_execz .LBB0_2488
	v_sub_f32_e32 v82, v239, v147
	v_mul_f32_e32 v82, 0x3fb8aa3b, v82
	v_exp_f32_e32 v82, v82
	s_nop 0
	v_mul_f32_e32 v82, v87, v82
	v_mul_f32_e32 v82, v139, v82
.LBB0_2488:
	s_or_b64 exec, exec, s[92:93]
	v_add_f32_e32 v83, v219, v82
	v_cndmask_b32_e64 v82, v82, v83, s[42:43]
	v_cvt_pk_bf16_f32 v82, v82, s0
	ds_write_b16 v217, v82 offset:18704
	v_mov_b32_e32 v82, 0
	v_mov_b32_e32 v83, 0
	s_and_saveexec_b64 s[92:93], s[44:45]
	s_cbranch_execz .LBB0_2490
	v_sub_f32_e32 v83, v240, v147
	v_mul_f32_e32 v83, 0x3fb8aa3b, v83
	v_exp_f32_e32 v83, v83
	s_nop 0
	v_mul_f32_e32 v83, v88, v83
	v_mul_f32_e32 v83, v139, v83
.LBB0_2490:
	s_or_b64 exec, exec, s[92:93]
	v_add_f32_e32 v84, v219, v83
	v_cndmask_b32_e64 v83, v83, v84, s[46:47]
	v_cvt_pk_bf16_f32 v83, v83, s0
	ds_write_b16 v217, v83 offset:18848
	s_and_saveexec_b64 s[92:93], s[48:49]
	s_cbranch_execz .LBB0_2492
	v_sub_f32_e32 v82, v241, v147
	v_mul_f32_e32 v82, 0x3fb8aa3b, v82
	v_exp_f32_e32 v82, v82
	s_nop 0
	v_mul_f32_e32 v82, v89, v82
	v_mul_f32_e32 v82, v139, v82
.LBB0_2492:
	s_or_b64 exec, exec, s[92:93]
	v_add_f32_e32 v83, v219, v82
	v_cndmask_b32_e64 v82, v82, v83, s[50:51]
	v_cvt_pk_bf16_f32 v82, v82, s0
	ds_write_b16 v217, v82 offset:18992
	v_mov_b32_e32 v82, 0
	v_mov_b32_e32 v83, 0
	s_and_saveexec_b64 s[92:93], s[52:53]
	s_cbranch_execz .LBB0_2494
	v_sub_f32_e32 v83, v246, v147
	v_mul_f32_e32 v83, 0x3fb8aa3b, v83
	v_exp_f32_e32 v83, v83
	s_nop 0
	v_mul_f32_e32 v83, v90, v83
	v_mul_f32_e32 v83, v139, v83
.LBB0_2494:
	s_or_b64 exec, exec, s[92:93]
	v_add_f32_e32 v84, v219, v83
	v_cndmask_b32_e64 v83, v83, v84, s[54:55]
	v_cvt_pk_bf16_f32 v83, v83, s0
	ds_write_b16 v217, v83 offset:19712
	s_and_saveexec_b64 s[92:93], s[56:57]
	s_cbranch_execz .LBB0_2496
	v_sub_f32_e32 v82, v247, v147
	v_mul_f32_e32 v82, 0x3fb8aa3b, v82
	v_exp_f32_e32 v82, v82
	s_nop 0
	v_mul_f32_e32 v82, v91, v82
	v_mul_f32_e32 v82, v139, v82
.LBB0_2496:
	s_or_b64 exec, exec, s[92:93]
	v_add_f32_e32 v83, v219, v82
	v_cndmask_b32_e64 v82, v82, v83, s[58:59]
	v_cvt_pk_bf16_f32 v82, v82, s0
	ds_write_b16 v217, v82 offset:19856
	v_mov_b32_e32 v82, 0
	v_mov_b32_e32 v83, 0
	s_and_saveexec_b64 s[92:93], s[60:61]
	s_cbranch_execz .LBB0_2498
	v_sub_f32_e32 v83, v248, v147
	v_mul_f32_e32 v83, 0x3fb8aa3b, v83
	v_exp_f32_e32 v83, v83
	s_nop 0
	v_mul_f32_e32 v83, v92, v83
	v_mul_f32_e32 v83, v139, v83
.LBB0_2498:
	s_or_b64 exec, exec, s[92:93]
	v_add_f32_e32 v84, v219, v83
	v_cndmask_b32_e64 v83, v83, v84, s[62:63]
	v_cvt_pk_bf16_f32 v83, v83, s0
	ds_write_b16 v217, v83 offset:20000
	s_and_saveexec_b64 s[92:93], s[64:65]
	s_cbranch_execz .LBB0_2500
	v_sub_f32_e32 v82, v249, v147
	v_mul_f32_e32 v82, 0x3fb8aa3b, v82
	v_exp_f32_e32 v82, v82
	s_nop 0
	v_mul_f32_e32 v82, v93, v82
	v_mul_f32_e32 v82, v139, v82
.LBB0_2500:
	s_or_b64 exec, exec, s[92:93]
	v_add_f32_e32 v83, v219, v82
	v_cndmask_b32_e64 v82, v82, v83, s[66:67]
	v_cvt_pk_bf16_f32 v82, v82, s0
	ds_write_b16 v217, v82 offset:20144
	v_mov_b32_e32 v82, 0
	v_mov_b32_e32 v83, 0
	s_and_saveexec_b64 s[92:93], s[68:69]
	s_cbranch_execz .LBB0_2502
	v_sub_f32_e32 v83, v250, v147
	v_mul_f32_e32 v83, 0x3fb8aa3b, v83
	v_exp_f32_e32 v83, v83
	s_nop 0
	v_mul_f32_e32 v83, v94, v83
	v_mul_f32_e32 v83, v139, v83
.LBB0_2502:
	s_or_b64 exec, exec, s[92:93]
	v_add_f32_e32 v84, v219, v83
	v_cndmask_b32_e64 v83, v83, v84, s[70:71]
	v_cvt_pk_bf16_f32 v83, v83, s0
	ds_write_b16 v217, v83 offset:20864
	s_and_saveexec_b64 s[92:93], s[72:73]
	s_cbranch_execz .LBB0_2504
	v_sub_f32_e32 v82, v251, v147
	v_mul_f32_e32 v82, 0x3fb8aa3b, v82
	v_exp_f32_e32 v82, v82
	s_nop 0
	v_mul_f32_e32 v82, v95, v82
	v_mul_f32_e32 v82, v139, v82
.LBB0_2504:
	s_or_b64 exec, exec, s[92:93]
	v_add_f32_e32 v83, v219, v82
	v_cndmask_b32_e64 v82, v82, v83, s[74:75]
	v_cvt_pk_bf16_f32 v82, v82, s0
	ds_write_b16 v217, v82 offset:21008
	v_mov_b32_e32 v82, 0
	v_mov_b32_e32 v83, 0
	s_and_saveexec_b64 s[92:93], s[76:77]
	s_cbranch_execz .LBB0_2506
	v_sub_f32_e32 v83, v252, v147
	v_mul_f32_e32 v83, 0x3fb8aa3b, v83
	v_exp_f32_e32 v83, v83
	s_nop 0
	v_mul_f32_e32 v83, v96, v83
	v_mul_f32_e32 v83, v139, v83
.LBB0_2506:
	s_or_b64 exec, exec, s[92:93]
	v_add_f32_e32 v84, v219, v83
	v_cndmask_b32_e64 v83, v83, v84, s[78:79]
	v_cvt_pk_bf16_f32 v83, v83, s0
	ds_write_b16 v217, v83 offset:21152
	s_and_saveexec_b64 s[92:93], s[80:81]
	s_cbranch_execz .LBB0_2508
	v_sub_f32_e32 v82, v253, v147
	v_mul_f32_e32 v82, 0x3fb8aa3b, v82
	v_exp_f32_e32 v82, v82
	s_nop 0
	v_mul_f32_e32 v82, v97, v82
	v_mul_f32_e32 v82, v139, v82

.LBB0_2688:
	s_or_b64 exec, exec, s[92:93]
	ds_read2_b64 v[66:69], v157 offset1:2
	v_cvt_pk_bf16_f32 v70, v50, v51
	v_cvt_pk_bf16_f32 v71, v52, v53
	v_cvt_pk_bf16_f32 v72, v54, v55
	v_cvt_pk_bf16_f32 v73, v56, v57
	ds_read2_b64 v[214:217], v157 offset0:4 offset1:6
	ds_read2_b64 v[234:237], v157 offset0:8 offset1:10
	ds_read2_b64 v[238:241], v157 offset0:12 offset1:14
	ds_read2_b64 v[246:249], v157 offset0:16 offset1:18
	v_cvt_pk_bf16_f32 v218, v58, v59
	v_cvt_pk_bf16_f32 v219, v60, v61
	v_cvt_pk_bf16_f32 v220, v62, v63
	s_waitcnt lgkmcnt(4)
	v_mfma_f32_32x32x16_bf16 v[66:81], v[66:69], v[70:73], 0
	v_cvt_pk_bf16_f32 v221, v64, v65
	s_waitcnt lgkmcnt(3)
	s_nop 0
	v_mfma_f32_32x32x16_bf16 v[66:81], v[214:217], v[218:221], v[66:81]
	ds_read2_b64 v[214:217], v157 offset0:20 offset1:22
	v_cvt_pk_bf16_f32 v218, v34, v35
	v_cvt_pk_bf16_f32 v219, v36, v37
	v_cvt_pk_bf16_f32 v220, v38, v39
	v_cvt_pk_bf16_f32 v221, v40, v41
	s_waitcnt lgkmcnt(3)
	s_nop 0
	v_mfma_f32_32x32x16_bf16 v[66:81], v[234:237], v[218:221], v[66:81]
	ds_read2_b64 v[234:237], v157 offset0:24 offset1:26
	v_cvt_pk_bf16_f32 v218, v42, v43
	v_cvt_pk_bf16_f32 v219, v44, v45
	v_cvt_pk_bf16_f32 v220, v46, v47
	v_cvt_pk_bf16_f32 v221, v48, v49
	s_waitcnt lgkmcnt(3)
	s_nop 0
	v_mfma_f32_32x32x16_bf16 v[66:81], v[238:241], v[218:221], v[66:81]
	ds_read2_b64 v[238:241], v157 offset0:28 offset1:30
	v_cvt_pk_bf16_f32 v218, v18, v19
	v_cvt_pk_bf16_f32 v219, v20, v21
	v_cvt_pk_bf16_f32 v220, v22, v23
	v_cvt_pk_bf16_f32 v221, v24, v25
	s_waitcnt lgkmcnt(3)
	s_nop 0
	v_mfma_f32_32x32x16_bf16 v[66:81], v[246:249], v[218:221], v[66:81]
	v_cvt_pk_bf16_f32 v218, v26, v27
	v_cvt_pk_bf16_f32 v219, v28, v29
	v_cvt_pk_bf16_f32 v220, v30, v31
	v_cvt_pk_bf16_f32 v221, v32, v33
	s_waitcnt lgkmcnt(2)
	s_nop 0
	v_mfma_f32_32x32x16_bf16 v[66:81], v[214:217], v[218:221], v[66:81]
	v_cvt_pk_bf16_f32 v218, v2, v3
	v_cvt_pk_bf16_f32 v219, v4, v5
	v_cvt_pk_bf16_f32 v220, v6, v7
	v_cvt_pk_bf16_f32 v221, v8, v9
	s_waitcnt lgkmcnt(1)
	s_nop 0
	v_mfma_f32_32x32x16_bf16 v[66:81], v[234:237], v[218:221], v[66:81]
	v_cvt_pk_bf16_f32 v218, v10, v11
	v_cvt_pk_bf16_f32 v219, v12, v13
	v_cvt_pk_bf16_f32 v220, v14, v15
	v_cvt_pk_bf16_f32 v221, v16, v17
	s_waitcnt lgkmcnt(0)
	s_barrier
	v_mfma_f32_32x32x16_bf16 v[66:81], v[238:241], v[218:221], v[66:81]
	s_and_saveexec_b64 s[92:93], s[4:5]
	s_xor_b64 s[92:93], exec, s[92:93]
	s_cbranch_execz .LBB0_2722
	ds_read_b32 v145, v163
	ds_read_b32 v141, v164
	ds_read_b32 v234, v175
	ds_read_b32 v235, v176
	ds_read_b32 v236, v177
	ds_read_b32 v237, v178
	ds_read_b32 v238, v179
	ds_read_b32 v239, v180
	ds_read_b32 v240, v181
	ds_read_b32 v241, v182
	ds_read_b32 v246, v183
	ds_read_b32 v247, v184
	ds_read_b32 v248, v185
	ds_read_b32 v249, v186
	s_waitcnt lgkmcnt(4)
	ds_read_b32 v250, v187
	ds_read_b32 v251, v188
	ds_read_b32 v252, v189
	ds_read_b32 v253, v190
	s_waitcnt lgkmcnt(0)
	v_mov_b32_e32 v147, 0
	v_mov_b32_e32 v214, 0
	s_and_saveexec_b64 s[94:95], s[18:19]
	s_cbranch_execz .LBB0_2691
	v_sub_f32_e32 v214, v234, v145
	v_mul_f32_e32 v214, 0x3fb8aa3b, v214
	v_exp_f32_e32 v214, v214
	s_nop 0
	v_mul_f32_e32 v82, v82, v214
	v_mul_f32_e32 v214, v141, v82
.LBB0_2691:
	s_or_b64 exec, exec, s[94:95]
	v_add_f32_e32 v82, v149, v214
	v_cndmask_b32_e64 v82, v214, v82, s[20:21]
	v_cvt_pk_bf16_f32 v82, v82, s0
	ds_write_b16 v213, v82 offset:17408
	s_and_saveexec_b64 s[94:95], s[22:23]
	s_cbranch_execz .LBB0_2693
	v_sub_f32_e32 v82, v235, v145
	v_mul_f32_e32 v82, 0x3fb8aa3b, v82
	v_exp_f32_e32 v82, v82
	s_nop 0
	v_mul_f32_e32 v82, v83, v82
	v_mul_f32_e32 v147, v141, v82
.LBB0_2693:
	s_or_b64 exec, exec, s[94:95]
	v_add_f32_e32 v82, v149, v147
	v_cndmask_b32_e64 v82, v147, v82, s[24:25]
	v_cvt_pk_bf16_f32 v82, v82, s0
	ds_write_b16 v213, v82 offset:17552
	v_mov_b32_e32 v82, 0
	v_mov_b32_e32 v83, 0
	s_and_saveexec_b64 s[94:95], s[26:27]
	s_cbranch_execz .LBB0_2695
	v_sub_f32_e32 v83, v236, v145
	v_mul_f32_e32 v83, 0x3fb8aa3b, v83
	v_exp_f32_e32 v83, v83
	s_nop 0
	v_mul_f32_e32 v83, v84, v83
	v_mul_f32_e32 v83, v141, v83
.LBB0_2695:
	s_or_b64 exec, exec, s[94:95]
	v_add_f32_e32 v84, v149, v83
	v_cndmask_b32_e64 v83, v83, v84, s[28:29]
	v_cvt_pk_bf16_f32 v83, v83, s0
	ds_write_b16 v213, v83 offset:17696
	s_and_saveexec_b64 s[94:95], s[30:31]
	s_cbranch_execz .LBB0_2697
	v_sub_f32_e32 v82, v237, v145
	v_mul_f32_e32 v82, 0x3fb8aa3b, v82
	v_exp_f32_e32 v82, v82
	s_nop 0
	v_mul_f32_e32 v82, v85, v82
	v_mul_f32_e32 v82, v141, v82
.LBB0_2697:
	s_or_b64 exec, exec, s[94:95]
	v_add_f32_e32 v83, v149, v82
	v_cndmask_b32_e64 v82, v82, v83, s[34:35]
	v_cvt_pk_bf16_f32 v82, v82, s0
	ds_write_b16 v213, v82 offset:17840
	v_mov_b32_e32 v82, 0
	v_mov_b32_e32 v83, 0
	s_and_saveexec_b64 s[94:95], s[36:37]
	s_cbranch_execz .LBB0_2699
	v_sub_f32_e32 v83, v238, v145
	v_mul_f32_e32 v83, 0x3fb8aa3b, v83
	v_exp_f32_e32 v83, v83
	s_nop 0
	v_mul_f32_e32 v83, v86, v83
	v_mul_f32_e32 v83, v141, v83
.LBB0_2699:
	s_or_b64 exec, exec, s[94:95]
	v_add_f32_e32 v84, v149, v83
	v_cndmask_b32_e64 v83, v83, v84, s[38:39]
	v_cvt_pk_bf16_f32 v83, v83, s0
	ds_write_b16 v213, v83 offset:18560
	s_and_saveexec_b64 s[94:95], s[40:41]
	s_cbranch_execz .LBB0_2701
	v_sub_f32_e32 v82, v239, v145
	v_mul_f32_e32 v82, 0x3fb8aa3b, v82
	v_exp_f32_e32 v82, v82
	s_nop 0
	v_mul_f32_e32 v82, v87, v82
	v_mul_f32_e32 v82, v141, v82
.LBB0_2701:
	s_or_b64 exec, exec, s[94:95]
	v_add_f32_e32 v83, v149, v82
	v_cndmask_b32_e64 v82, v82, v83, s[42:43]
	v_cvt_pk_bf16_f32 v82, v82, s0
	ds_write_b16 v213, v82 offset:18704
	v_mov_b32_e32 v82, 0
	v_mov_b32_e32 v83, 0
	s_and_saveexec_b64 s[94:95], s[44:45]
	s_cbranch_execz .LBB0_2703
	v_sub_f32_e32 v83, v240, v145
	v_mul_f32_e32 v83, 0x3fb8aa3b, v83
	v_exp_f32_e32 v83, v83
	s_nop 0
	v_mul_f32_e32 v83, v88, v83
	v_mul_f32_e32 v83, v141, v83
.LBB0_2703:
	s_or_b64 exec, exec, s[94:95]
	v_add_f32_e32 v84, v149, v83
	v_cndmask_b32_e64 v83, v83, v84, s[46:47]
	v_cvt_pk_bf16_f32 v83, v83, s0
	ds_write_b16 v213, v83 offset:18848
	s_and_saveexec_b64 s[94:95], s[48:49]
	s_cbranch_execz .LBB0_2705
	v_sub_f32_e32 v82, v241, v145
	v_mul_f32_e32 v82, 0x3fb8aa3b, v82
	v_exp_f32_e32 v82, v82
	s_nop 0
	v_mul_f32_e32 v82, v89, v82
	v_mul_f32_e32 v82, v141, v82
.LBB0_2705:
	s_or_b64 exec, exec, s[94:95]
	v_add_f32_e32 v83, v149, v82
	v_cndmask_b32_e64 v82, v82, v83, s[50:51]
	v_cvt_pk_bf16_f32 v82, v82, s0
	ds_write_b16 v213, v82 offset:18992
	v_mov_b32_e32 v82, 0
	v_mov_b32_e32 v83, 0
	s_and_saveexec_b64 s[94:95], s[52:53]
	s_cbranch_execz .LBB0_2707
	v_sub_f32_e32 v83, v246, v145
	v_mul_f32_e32 v83, 0x3fb8aa3b, v83
	v_exp_f32_e32 v83, v83
	s_nop 0
	v_mul_f32_e32 v83, v90, v83
	v_mul_f32_e32 v83, v141, v83
.LBB0_2707:
	s_or_b64 exec, exec, s[94:95]
	v_add_f32_e32 v84, v149, v83
	v_cndmask_b32_e64 v83, v83, v84, s[54:55]
	v_cvt_pk_bf16_f32 v83, v83, s0
	ds_write_b16 v213, v83 offset:19712
	s_and_saveexec_b64 s[94:95], s[56:57]
	s_cbranch_execz .LBB0_2709
	v_sub_f32_e32 v82, v247, v145
	v_mul_f32_e32 v82, 0x3fb8aa3b, v82
	v_exp_f32_e32 v82, v82
	s_nop 0
	v_mul_f32_e32 v82, v91, v82
	v_mul_f32_e32 v82, v141, v82
.LBB0_2709:
	s_or_b64 exec, exec, s[94:95]
	v_add_f32_e32 v83, v149, v82
	v_cndmask_b32_e64 v82, v82, v83, s[58:59]
	v_cvt_pk_bf16_f32 v82, v82, s0
	ds_write_b16 v213, v82 offset:19856
	v_mov_b32_e32 v82, 0
	v_mov_b32_e32 v83, 0
	s_and_saveexec_b64 s[94:95], s[60:61]
	s_cbranch_execz .LBB0_2711
	v_sub_f32_e32 v83, v248, v145
	v_mul_f32_e32 v83, 0x3fb8aa3b, v83
	v_exp_f32_e32 v83, v83
	s_nop 0
	v_mul_f32_e32 v83, v92, v83
	v_mul_f32_e32 v83, v141, v83
.LBB0_2711:
	s_or_b64 exec, exec, s[94:95]
	v_add_f32_e32 v84, v149, v83
	v_cndmask_b32_e64 v83, v83, v84, s[62:63]
	v_cvt_pk_bf16_f32 v83, v83, s0
	ds_write_b16 v213, v83 offset:20000
	s_and_saveexec_b64 s[94:95], s[64:65]
	s_cbranch_execz .LBB0_2713
	v_sub_f32_e32 v82, v249, v145
	v_mul_f32_e32 v82, 0x3fb8aa3b, v82
	v_exp_f32_e32 v82, v82
	s_nop 0
	v_mul_f32_e32 v82, v93, v82
	v_mul_f32_e32 v82, v141, v82
.LBB0_2713:
	s_or_b64 exec, exec, s[94:95]
	v_add_f32_e32 v83, v149, v82
	v_cndmask_b32_e64 v82, v82, v83, s[66:67]
	v_cvt_pk_bf16_f32 v82, v82, s0
	ds_write_b16 v213, v82 offset:20144
	v_mov_b32_e32 v82, 0
	v_mov_b32_e32 v83, 0
	s_and_saveexec_b64 s[94:95], s[68:69]
	s_cbranch_execz .LBB0_2715
	v_sub_f32_e32 v83, v250, v145
	v_mul_f32_e32 v83, 0x3fb8aa3b, v83
	v_exp_f32_e32 v83, v83
	s_nop 0
	v_mul_f32_e32 v83, v94, v83
	v_mul_f32_e32 v83, v141, v83
.LBB0_2715:
	s_or_b64 exec, exec, s[94:95]
	v_add_f32_e32 v84, v149, v83
	v_cndmask_b32_e64 v83, v83, v84, s[70:71]
	v_cvt_pk_bf16_f32 v83, v83, s0
	ds_write_b16 v213, v83 offset:20864
	s_and_saveexec_b64 s[94:95], s[72:73]
	s_cbranch_execz .LBB0_2717
	v_sub_f32_e32 v82, v251, v145
	v_mul_f32_e32 v82, 0x3fb8aa3b, v82
	v_exp_f32_e32 v82, v82
	s_nop 0
	v_mul_f32_e32 v82, v95, v82
	v_mul_f32_e32 v82, v141, v82
.LBB0_2717:
	s_or_b64 exec, exec, s[94:95]
	v_add_f32_e32 v83, v149, v82
	v_cndmask_b32_e64 v82, v82, v83, s[74:75]
	v_cvt_pk_bf16_f32 v82, v82, s0
	ds_write_b16 v213, v82 offset:21008
	v_mov_b32_e32 v82, 0
	v_mov_b32_e32 v83, 0
	s_and_saveexec_b64 s[94:95], s[76:77]
	s_cbranch_execz .LBB0_2719
	v_sub_f32_e32 v83, v252, v145
	v_mul_f32_e32 v83, 0x3fb8aa3b, v83
	v_exp_f32_e32 v83, v83
	s_nop 0
	v_mul_f32_e32 v83, v96, v83
	v_mul_f32_e32 v83, v141, v83
.LBB0_2719:
	s_or_b64 exec, exec, s[94:95]
	v_add_f32_e32 v84, v149, v83
	v_cndmask_b32_e64 v83, v83, v84, s[78:79]
	v_cvt_pk_bf16_f32 v83, v83, s0
	ds_write_b16 v213, v83 offset:21152
	s_and_saveexec_b64 s[94:95], s[80:81]
	s_cbranch_execz .LBB0_2721
	v_sub_f32_e32 v82, v253, v145
	v_mul_f32_e32 v82, 0x3fb8aa3b, v82
	v_exp_f32_e32 v82, v82
	s_nop 0
	v_mul_f32_e32 v82, v97, v82
	v_mul_f32_e32 v82, v141, v82
